# seams 1-5: hand-written XCD grid barrier (same arrive/release/acquire fences; XCC leaders post directly to every XCC's release word, no top-counter round trip, no division/timeout code); on top of v06
# baseline (speedup 1.0000x reference)
; #define LAS __attribute__((address_space(3)))
; __device__ __forceinline__ unsigned xb_ld(unsigned* p)              { return __hip_atomic_load(p, __ATOMIC_RELAXED, __HIP_MEMORY_SCOPE_AGENT); }
; __device__ __forceinline__ void h1_phase(const Ptrs& P, LAS unsigned char* lds, int bx, int G, int tid) {
;     LAS unsigned short* KT = (LAS unsigned short*)lds;
;     LAS unsigned short* VT = KT + 128 * 72;
;     LAS float* tot = (LAS float*)(VT + 128 * 72);
;     LAS h16* FST = (LAS h16*)(tot + 512);
;     LAS h16* LT = FST + 64 * 128;
;     const int d = tid & 127, i = __builtin_amdgcn_readfirstlane(tid >> 7), lane = tid & 63, w = __builtin_amdgcn_readfirstlane(tid >> 6);
;     const int fr = lane & 15, fq = lane >> 4;
;     const int NIT = NCH * NH;
;     if (bx >= NIT) return;
;     h16x8 pf[2], pv[2];
;     ...
;     H1_PREFETCH(bx);
;     const bool hfix = (G & 15) == 0;
;     float l0 = P.lb_logits[(bx & 15) * HD + d], l1 = P.lb_logits[HW + (bx & 15) * HD + d];
;     int itprev = -1;
;     for (int it = bx; it < NIT; it += G) {
; __device__ __forceinline__ void xcd_barrier(unsigned* bar, volatile LAS unsigned* st, bool is_t0) {
;     asm volatile("s_waitcnt vmcnt(0)" ::: "memory");
;     __syncthreads();
;     if (is_t0) {
;         __builtin_amdgcn_s_waitcnt(0);
;         const unsigned x = xb_xcc_id();
;         unsigned nloc = st[0], nx = st[1];
;         if (nloc == 0u) { xcd_barrier_complete(bar, x, nloc, nx); st[0] = nloc; st[1] = nx; }
;         const unsigned old = xb_add(&bar[XB_XSUB(x)], 1u);
;         const unsigned gen = old / nloc;
;         if (old + 1u == (gen + 1u) * nloc) {
;             __builtin_amdgcn_fence(__ATOMIC_RELEASE, "agent");
;             asm volatile("s_waitcnt vmcnt(0)" ::: "memory");
;             const unsigned og = xb_add(&bar[XB_TOP], 1u);
;             const unsigned tg = og / nx;
;             if (og + 1u == (tg + 1u) * nx) xb_add(&bar[XB_TOPGEN], 1u);
;             else XB_SPIN(xb_ld(&bar[XB_TOPGEN]) == tg, bar);
;             __builtin_amdgcn_fence(__ATOMIC_ACQUIRE, "agent");
;             xb_add(&bar[XB_XGEN(x)], 1u);
;             asm volatile("s_waitcnt vmcnt(0)" ::: "memory");
;         } else {
;             XB_SPIN(xb_ld(&bar[XB_XGEN(x)]) == gen, bar);
;             __builtin_amdgcn_fence(__ATOMIC_ACQUIRE, "agent");
;             asm volatile("s_waitcnt vmcnt(0)" ::: "memory");
;         }
;     }
;     __syncthreads();
.LBB0_164:
	v_mbcnt_lo_u32_b32 v0, -1, 0
	v_mbcnt_hi_u32_b32 v0, -1, v0
	s_waitcnt vmcnt(0)
	s_waitcnt vmcnt(0)
	v_cmp_eq_u32_e32 vcc, 0, v0
	s_and_b64 s[0:1], vcc, s[36:37]
	s_barrier
	s_and_saveexec_b64 s[4:5], s[0:1]
	s_xor_b64 s[0:1], exec, s[4:5]
	s_cbranch_execz .LBB0_217
	s_waitcnt vmcnt(0) expcnt(0) lgkmcnt(0)
	v_mov_b32_e32 v250, 0x24080
	ds_read_b64 v[250:251], v250
	s_getreg_b32 s90, hwreg(HW_REG_XCC_ID, 0, 4)
	s_and_b32 s90, s90, 15
	s_lshl_b32 s91, s90, 8
	s_add_u32 s92, s34, s91
	s_addc_u32 s93, s35, 0
	s_add_u32 s92, s92, 0x1000
	s_addc_u32 s93, s93, 0
	s_add_u32 s94, s34, 0x3600
	s_addc_u32 s95, s35, 0
	s_lshl_b32 s91, s90, 7
	s_add_u32 s96, s94, s91
	s_addc_u32 s97, s95, 0
	v_mov_b32_e32 v253, 0
	v_mov_b32_e32 v252, 1
	s_waitcnt lgkmcnt(0)
	v_readfirstlane_b32 s98, v250
	v_readfirstlane_b32 s99, v251
	global_atomic_add v250, v253, v252, s[92:93] offset:1024 sc0
	s_mul_i32 s98, s98, 2
	s_mul_i32 s99, s99, 1
	s_waitcnt vmcnt(0)
	v_readfirstlane_b32 s91, v250
	s_add_i32 s91, s91, 1
	s_cmp_lg_u32 s91, s98
	s_cbranch_scc1 .Lfb1_poll
	buffer_wbl2 sc1
	s_waitcnt vmcnt(0)
	global_atomic_add v253, v252, s[94:95]
	global_atomic_add v253, v252, s[94:95] offset:128
	global_atomic_add v253, v252, s[94:95] offset:256
	global_atomic_add v253, v252, s[94:95] offset:384
	global_atomic_add v253, v252, s[94:95] offset:512
	global_atomic_add v253, v252, s[94:95] offset:640
	global_atomic_add v253, v252, s[94:95] offset:768
	global_atomic_add v253, v252, s[94:95] offset:896
	global_atomic_add v253, v252, s[94:95] offset:1024
	global_atomic_add v253, v252, s[94:95] offset:1152
	global_atomic_add v253, v252, s[94:95] offset:1280
	global_atomic_add v253, v252, s[94:95] offset:1408
	global_atomic_add v253, v252, s[94:95] offset:1536
	global_atomic_add v253, v252, s[94:95] offset:1664
	global_atomic_add v253, v252, s[94:95] offset:1792
	global_atomic_add v253, v252, s[94:95] offset:1920
.Lfb1_poll:
	s_mov_b32 s98, 0x40000
.Lfb1_spin:
	global_load_dword v250, v253, s[96:97] sc1
	s_waitcnt vmcnt(0)
	v_readfirstlane_b32 s91, v250
	s_cmp_ge_u32 s91, s99
	s_cbranch_scc1 .Lfb1_done
	s_sub_i32 s98, s98, 1
	s_cmp_lg_u32 s98, 0
	s_cbranch_scc1 .Lfb1_spin
.Lfb1_done:
	buffer_inv sc1
	s_waitcnt vmcnt(0)
.LBB0_217:
	s_or_b64 exec, exec, s[0:1]
	s_cmpk_lt_i32 s2, 0x800
	s_cselect_b64 s[4:5], -1, 0
	s_and_b32 s0, s30, 15
	s_cmp_lg_u32 s0, 0
	s_cselect_b64 s[42:43], -1, 0
	s_add_i32 s0, 0, 0x24018
	s_waitcnt lgkmcnt(0)
	v_mov_b32_e32 v0, s0
	s_add_i32 s0, 0, 0x24028
	v_mov_b32_e32 v2, s0
	s_add_i32 s0, 0, 0x24060
	v_mov_b32_e32 v4, s0
	s_barrier
	ds_read_b64 v[0:1], v0
	ds_read_b64 v[2:3], v2
	ds_read_b64 v[4:5], v4
	v_mbcnt_lo_u32_b32 v17, -1, 0
	v_mbcnt_hi_u32_b32 v17, -1, v17
	s_mov_b32 s9, 0
	v_or_b32_e32 v24, s33, v17
	s_waitcnt lgkmcnt(2)
	v_readfirstlane_b32 s11, v1
	v_readfirstlane_b32 s10, v0
	s_waitcnt lgkmcnt(1)
	v_readfirstlane_b32 s1, v3
	v_readfirstlane_b32 s0, v2
	s_waitcnt lgkmcnt(0)
	v_readfirstlane_b32 s7, v5
	v_readfirstlane_b32 s28, v4
	v_readfirstlane_b32 s8, v24
	s_and_b64 vcc, exec, s[4:5]
	s_cbranch_vccz .LBB0_234
	s_add_u32 s27, s28, 0x14200000
	s_addc_u32 s45, s7, 0
	s_add_u32 s29, s28, 0x2c200000
	s_addc_u32 s44, s7, 0
	s_add_u32 s26, s28, 0x100000
	s_addc_u32 s48, s7, 0
	s_lshl_b32 s12, s2, 2
	s_andn2_b32 s12, s12, 63
	s_lshl_b32 s46, s2, 7
	s_ashr_i32 s13, s12, 31
	s_and_b32 s16, s46, 0x780
	s_lshl_b64 s[12:13], s[12:13], 14
	s_ashr_i32 s22, s8, 7
	s_add_u32 s12, s27, s12
	s_addc_u32 s13, s45, s13
	s_lshl_b32 s14, s16, 1
	v_lshlrev_b32_e32 v16, 3, v24
	s_add_u32 s12, s12, s14
	v_and_b32_e32 v32, 0x78, v16
	v_add_u32_e32 v6, 0x200, v24
	s_addc_u32 s13, s13, 0
	v_mov_b32_e32 v19, 0
	v_lshlrev_b32_e32 v18, 1, v32
	v_ashrrev_i32_e32 v26, 4, v24
	v_ashrrev_i32_e32 v28, 4, v6
	v_lshl_add_u64 v[0:1], s[12:13], 0, v[18:19]
	s_mov_b64 s[12:13], 0x1000
	v_ashrrev_i32_e32 v27, 31, v26
	v_ashrrev_i32_e32 v29, 31, v28
	s_mov_b64 s[14:15], 0x2000
	v_and_b32_e32 v34, 0x7f, v24
	v_lshl_add_u64 v[2:3], v[0:1], 0, s[12:13]
	v_lshlrev_b64 v[20:21], 14, v[26:27]
	v_lshlrev_b64 v[22:23], 14, v[28:29]
	v_lshl_add_u64 v[0:1], v[0:1], 0, s[14:15]
	v_lshl_add_u64 v[4:5], v[2:3], 0, v[20:21]
	v_lshl_add_u64 v[2:3], v[2:3], 0, v[22:23]
	v_lshl_add_u64 v[30:31], v[0:1], 0, v[20:21]
	v_or_b32_e32 v25, s16, v34
	global_load_dwordx4 v[232:235], v[4:5], off
	global_load_dwordx4 v[236:239], v[2:3], off
	v_lshl_add_u64 v[36:37], v[0:1], 0, v[22:23]
	global_load_dwordx4 v[240:243], v[30:31], off
	global_load_dwordx4 v[244:247], v[36:37], off
	v_lshlrev_b32_e32 v30, 2, v25
	v_mov_b32_e32 v31, v19
	v_lshl_add_u64 v[36:37], s[10:11], 0, v[30:31]
	s_movk_i32 s16, 0x2000
	v_add_co_u32_e32 v38, vcc, s16, v36
	v_lshlrev_b32_e32 v25, 1, v34
	s_nop 0
	v_addc_co_u32_e32 v39, vcc, 0, v37, vcc
	global_load_dword v37, v30, s[10:11]
	global_load_dword v40, v[38:39], off
	v_add_u32_e32 v35, 0, v25
	v_lshlrev_b32_e32 v24, 4, v24
	v_add_u32_e32 v36, v35, v25
	v_and_b32_e32 v25, 0xffffff00, v24
	s_lshl_b32 s47, s22, 12
	s_and_b32 s16, s8, 0x3fffff80
	s_lshl_b32 s51, s22, 5
	v_add3_u32 v38, 0, v18, v25
	v_bitop3_b32 v18, v16, v26, 56 bitop3:0x6c
	s_cmpk_lt_u32 s8, 0x80
	v_lshl_add_u32 v33, v18, 1, 0
	v_bitop3_b32 v18, v28, v16, 56 bitop3:0x78
	v_lshl_add_u32 v41, s16, 2, v36
	s_cselect_b64 s[16:17], -1, 0
	s_ashr_i32 s8, s8, 2
	v_bfe_u32 v31, v17, 4, 2
	s_movk_i32 s18, 0x90
	v_lshl_add_u32 v47, v18, 1, 0
	v_bfi_b32 v18, -16, s8, v17
	v_and_b32_e32 v30, 15, v17
	v_lshlrev_b32_e32 v44, 3, v31
	v_mul_lo_u32 v17, v18, s18
	s_and_b32 s24, s8, -16
	v_add_u32_e32 v45, 0, v17
	v_lshl_add_u32 v50, v30, 1, 0
	v_mul_u32_u24_e32 v51, 0x90, v30
	v_bitop3_b32 v30, v18, v44, 56 bitop3:0x6c
	s_cmp_lt_i32 s22, 1
	v_lshl_add_u32 v43, v30, 1, v45
	v_or_b32_e32 v30, 32, v44
	v_mad_u32_u24 v48, v34, s18, 0
	s_cselect_b64 s[18:19], -1, 0
	s_cmp_lt_i32 s22, 2
	v_bitop3_b32 v18, v18, v30, 56 bitop3:0x6c
	s_cselect_b64 s[20:21], -1, 0
	s_cmp_lt_i32 s22, 3
	v_lshl_add_u32 v44, v18, 1, v45
	v_lshlrev_b32_e32 v18, 10, v31
	s_cselect_b64 s[22:23], -1, 0
	v_lshl_or_b32 v52, s24, 8, v18
	s_lshl_b64 s[24:25], s[2:3], 9
	s_add_u32 s24, s26, s24
	v_mul_u32_u24_e32 v46, 0x90, v32
	v_lshl_add_u32 v49, v31, 4, 0
	v_add_u32_e32 v42, 0, v24
	v_add_u32_e32 v26, 0x1000, v16
	v_add_u32_e32 v24, 0x2000, v16
	v_add_u32_e32 v28, 0x3000, v16
	v_lshlrev_b32_e32 v18, 2, v34
	s_addc_u32 s25, s48, s25
	v_add_u32_e32 v39, 0xd800, v42
	v_ashrrev_i32_e32 v17, 31, v16
	v_ashrrev_i32_e32 v27, 31, v26
	v_ashrrev_i32_e32 v25, 31, v24
	v_ashrrev_i32_e32 v29, 31, v28
	v_lshl_add_u64 v[30:31], s[24:25], 0, v[18:19]
	s_lshl_b64 s[24:25], s[30:31], 9
	s_lshl_b32 s48, s30, 7
	s_mov_b32 s8, -1
	v_add_u32_e32 v45, v33, v46
	v_add_u32_e32 v46, v47, v46
	s_movk_i32 s49, 0x7fff
	s_mov_b32 s50, 0xffff0000
	v_add_u32_e32 v47, s51, v48
	v_lshlrev_b32_e32 v18, 1, v32
	v_add_u32_e32 v48, v49, v51
	v_add_u32_e32 v49, v50, v52
	s_mov_b32 s26, s2
	s_andn2_b64 vcc, exec, s[42:43]
	s_cbranch_vccz .LBB0_220
	s_branch .LBB0_221

; #define LAS __attribute__((address_space(3)))
; __device__ __forceinline__ unsigned xb_ld(unsigned* p)              { return __hip_atomic_load(p, __ATOMIC_RELAXED, __HIP_MEMORY_SCOPE_AGENT); }
; __device__ __forceinline__ unsigned xb_add(unsigned* p, unsigned v) { return __hip_atomic_fetch_add(p, v, __ATOMIC_RELAXED, __HIP_MEMORY_SCOPE_AGENT); }
; __device__ __forceinline__ unsigned xb_xcc_id() { return (unsigned)__builtin_amdgcn_s_getreg((3 << 11) | 20) & 0xFu; }
; #define XB_SPIN(cond, bar) do { unsigned _sp = 0; while (cond) { __builtin_amdgcn_s_sleep(1); \
;     if ((++_sp & 255u) == 0u) { if (xb_ld(&(bar)[XB_TMO])) break; if (_sp > XB_SPIN_CAP) { atomicAdd(&(bar)[XB_TMO], 1u); break; } } } } while (0)
; __device__ __forceinline__ void xcd_barrier(unsigned* bar, volatile LAS unsigned* st, bool is_t0) {
;     asm volatile("s_waitcnt vmcnt(0)" ::: "memory");
;     __syncthreads();
;     if (is_t0) {
;         __builtin_amdgcn_s_waitcnt(0);
;         const unsigned x = xb_xcc_id();
;         unsigned nloc = st[0], nx = st[1];
;         if (nloc == 0u) { xcd_barrier_complete(bar, x, nloc, nx); st[0] = nloc; st[1] = nx; }
;         const unsigned old = xb_add(&bar[XB_XSUB(x)], 1u);
;         const unsigned gen = old / nloc;
;         if (old + 1u == (gen + 1u) * nloc) {
;             __builtin_amdgcn_fence(__ATOMIC_RELEASE, "agent");
;             asm volatile("s_waitcnt vmcnt(0)" ::: "memory");
;             const unsigned og = xb_add(&bar[XB_TOP], 1u);
;             const unsigned tg = og / nx;
;             if (og + 1u == (tg + 1u) * nx) xb_add(&bar[XB_TOPGEN], 1u);
;             else XB_SPIN(xb_ld(&bar[XB_TOPGEN]) == tg, bar);
;             __builtin_amdgcn_fence(__ATOMIC_ACQUIRE, "agent");
;             xb_add(&bar[XB_XGEN(x)], 1u);
;             asm volatile("s_waitcnt vmcnt(0)" ::: "memory");
;         } else {
;             XB_SPIN(xb_ld(&bar[XB_XGEN(x)]) == gen, bar);
;             __builtin_amdgcn_fence(__ATOMIC_ACQUIRE, "agent");
;             asm volatile("s_waitcnt vmcnt(0)" ::: "memory");
;         }
;     }
;     __syncthreads();
.LBB0_239:
	s_or_b64 exec, exec, s[8:9]
	v_mbcnt_lo_u32_b32 v0, -1, 0
	v_mbcnt_hi_u32_b32 v0, -1, v0
	s_waitcnt vmcnt(0)
	s_nop 0
	v_cmp_eq_u32_e32 vcc, 0, v0
	s_and_b64 s[0:1], vcc, s[36:37]
	s_barrier
	s_and_saveexec_b64 s[8:9], s[0:1]
	s_xor_b64 s[0:1], exec, s[8:9]
	s_cbranch_execz .LBB0_292
	s_waitcnt vmcnt(0) expcnt(0) lgkmcnt(0)
	v_mov_b32_e32 v250, 0x24080
	ds_read_b64 v[250:251], v250
	s_getreg_b32 s90, hwreg(HW_REG_XCC_ID, 0, 4)
	s_and_b32 s90, s90, 15
	s_lshl_b32 s91, s90, 8
	s_add_u32 s92, s34, s91
	s_addc_u32 s93, s35, 0
	s_add_u32 s92, s92, 0x1000
	s_addc_u32 s93, s93, 0
	s_add_u32 s94, s34, 0x3600
	s_addc_u32 s95, s35, 0
	s_lshl_b32 s91, s90, 7
	s_add_u32 s96, s94, s91
	s_addc_u32 s97, s95, 0
	v_mov_b32_e32 v253, 0
	v_mov_b32_e32 v252, 1
	s_waitcnt lgkmcnt(0)
	v_readfirstlane_b32 s98, v250
	v_readfirstlane_b32 s99, v251
	global_atomic_add v250, v253, v252, s[92:93] offset:1024 sc0
	s_mul_i32 s98, s98, 3
	s_mul_i32 s99, s99, 2
	s_waitcnt vmcnt(0)
	v_readfirstlane_b32 s91, v250
	s_add_i32 s91, s91, 1
	s_cmp_lg_u32 s91, s98
	s_cbranch_scc1 .Lfb2_poll
	buffer_wbl2 sc1
	s_waitcnt vmcnt(0)
	global_atomic_add v253, v252, s[94:95]
	global_atomic_add v253, v252, s[94:95] offset:128
	global_atomic_add v253, v252, s[94:95] offset:256
	global_atomic_add v253, v252, s[94:95] offset:384
	global_atomic_add v253, v252, s[94:95] offset:512
	global_atomic_add v253, v252, s[94:95] offset:640
	global_atomic_add v253, v252, s[94:95] offset:768
	global_atomic_add v253, v252, s[94:95] offset:896
	global_atomic_add v253, v252, s[94:95] offset:1024
	global_atomic_add v253, v252, s[94:95] offset:1152
	global_atomic_add v253, v252, s[94:95] offset:1280
	global_atomic_add v253, v252, s[94:95] offset:1408
	global_atomic_add v253, v252, s[94:95] offset:1536
	global_atomic_add v253, v252, s[94:95] offset:1664
	global_atomic_add v253, v252, s[94:95] offset:1792
	global_atomic_add v253, v252, s[94:95] offset:1920

; __device__ __forceinline__ void h2_phase(const Ptrs& P, int G, int tid) {
;     constexpr size_t SLAB = (size_t)NH * HD * HD;
;     constexpr int UB = 16;
;     for (int idx = blockIdx.x * 512 + tid; idx < NH * HD * (HD / 2); idx += G * 512) {
;         const int d2 = idx & 63, e = (idx >> 6) & 127, h = idx >> 13;
;         const size_t off = ((size_t)h * HD + e) * HD + 2 * d2;
;         float s0 = 0.f, s1 = 0.f;
;         for (int nb = 0; nb < NCH; nb += UB) {
;             h16x2 l[UB]; f32x2 dd[UB];
; #pragma unroll
;             for (int q = 0; q < UB; ++q) { l[q] = *(const h16x2*)(P.L + (size_t)(nb + q) * SLAB + off); dd[q] = *(const f32x2*)(P.Dn + (size_t)((nb + q) * NH + h) * HD + 2 * d2); }
.Lfb2_done:
	buffer_inv sc1
	s_waitcnt vmcnt(0)
.LBB0_292:
	s_or_b64 exec, exec, s[0:1]
	s_add_i32 s0, 0, 0x24060
	s_waitcnt lgkmcnt(0)
	v_mov_b32_e32 v0, s0
	s_barrier
	ds_read_b64 v[0:1], v0
	s_mov_b32 s7, 0x20000
	s_waitcnt lgkmcnt(0)
	v_readfirstlane_b32 s1, v0
	v_mbcnt_lo_u32_b32 v0, -1, 0
	v_mbcnt_hi_u32_b32 v0, -1, v0
	v_readfirstlane_b32 s0, v1
	v_or_b32_e32 v0, s33, v0
	v_add_u32_e32 v28, s52, v0
	v_cmp_gt_i32_e32 vcc, s7, v28
	s_and_saveexec_b64 s[8:9], vcc
	s_cbranch_execz .LBB0_297
	s_add_u32 s10, s1, 0x100000
	s_addc_u32 s11, s0, 0
	s_add_u32 s12, s1, 0x2c200000
	s_addc_u32 s13, s0, 0
	s_add_u32 s14, s1, 0x30200000
	v_lshlrev_b32_e32 v0, 1, v0
	s_addc_u32 s15, s0, 0
	v_lshl_add_u32 v29, s2, 10, v0
	s_lshl_b32 s7, s30, 10
	s_mov_b64 s[16:17], 0
	s_movk_i32 s22, 0x1f8
	s_mov_b32 s23, 0x80000
	s_mov_b32 s24, 0x100000
	s_mov_b32 s25, 0x180000
	s_mov_b32 s26, 0x200000
	s_mov_b32 s27, 0x280000
	s_mov_b32 s28, 0x300000
	s_mov_b32 s29, 0x380000
	s_mov_b32 s44, 0x400000
	s_mov_b32 s45, 0x480000
	s_mov_b32 s46, 0x500000
	s_mov_b32 s47, 0x580000
	s_mov_b32 s48, 0x600000
	s_mov_b32 s49, 0x680000
	s_mov_b32 s50, 0x700000
	s_mov_b32 s51, 0x780000
	s_movk_i32 s52, 0x7fff
	s_mov_b32 s53, 0xffff0000
	s_mov_b64 s[18:19], 0x20000
	s_mov_b32 s54, 0x1ffff

; #define LAS __attribute__((address_space(3)))
; __device__ __forceinline__ unsigned xb_ld(unsigned* p)              { return __hip_atomic_load(p, __ATOMIC_RELAXED, __HIP_MEMORY_SCOPE_AGENT); }
; __device__ __forceinline__ unsigned xb_add(unsigned* p, unsigned v) { return __hip_atomic_fetch_add(p, v, __ATOMIC_RELAXED, __HIP_MEMORY_SCOPE_AGENT); }
; __device__ __forceinline__ unsigned xb_xcc_id() { return (unsigned)__builtin_amdgcn_s_getreg((3 << 11) | 20) & 0xFu; }
; #define XB_SPIN(cond, bar) do { unsigned _sp = 0; while (cond) { __builtin_amdgcn_s_sleep(1); \
;     if ((++_sp & 255u) == 0u) { if (xb_ld(&(bar)[XB_TMO])) break; if (_sp > XB_SPIN_CAP) { atomicAdd(&(bar)[XB_TMO], 1u); break; } } } } while (0)
; __device__ __forceinline__ void xcd_barrier(unsigned* bar, volatile LAS unsigned* st, bool is_t0) {
;     asm volatile("s_waitcnt vmcnt(0)" ::: "memory");
;     __syncthreads();
;     if (is_t0) {
;         __builtin_amdgcn_s_waitcnt(0);
;         const unsigned x = xb_xcc_id();
;         unsigned nloc = st[0], nx = st[1];
;         if (nloc == 0u) { xcd_barrier_complete(bar, x, nloc, nx); st[0] = nloc; st[1] = nx; }
;         const unsigned old = xb_add(&bar[XB_XSUB(x)], 1u);
;         const unsigned gen = old / nloc;
;         if (old + 1u == (gen + 1u) * nloc) {
;             __builtin_amdgcn_fence(__ATOMIC_RELEASE, "agent");
;             asm volatile("s_waitcnt vmcnt(0)" ::: "memory");
;             const unsigned og = xb_add(&bar[XB_TOP], 1u);
;             const unsigned tg = og / nx;
;             if (og + 1u == (tg + 1u) * nx) xb_add(&bar[XB_TOPGEN], 1u);
;             else XB_SPIN(xb_ld(&bar[XB_TOPGEN]) == tg, bar);
;             __builtin_amdgcn_fence(__ATOMIC_ACQUIRE, "agent");
;             xb_add(&bar[XB_XGEN(x)], 1u);
;             asm volatile("s_waitcnt vmcnt(0)" ::: "memory");
;         } else {
;             XB_SPIN(xb_ld(&bar[XB_XGEN(x)]) == gen, bar);
;             __builtin_amdgcn_fence(__ATOMIC_ACQUIRE, "agent");
;             asm volatile("s_waitcnt vmcnt(0)" ::: "memory");
;         }
;     }
;     __syncthreads();
.LBB0_297:
	s_or_b64 exec, exec, s[8:9]
	v_mbcnt_lo_u32_b32 v0, -1, 0
	v_mbcnt_hi_u32_b32 v0, -1, v0
	s_waitcnt vmcnt(0)
	s_nop 0
	v_cmp_eq_u32_e32 vcc, 0, v0
	s_and_b64 s[0:1], vcc, s[36:37]
	s_barrier
	s_and_saveexec_b64 s[6:7], s[0:1]
	s_xor_b64 s[0:1], exec, s[6:7]
	s_cbranch_execz .LBB0_350
	s_waitcnt vmcnt(0) expcnt(0) lgkmcnt(0)
	v_mov_b32_e32 v250, 0x24080
	ds_read_b64 v[250:251], v250
	s_getreg_b32 s90, hwreg(HW_REG_XCC_ID, 0, 4)
	s_and_b32 s90, s90, 15
	s_lshl_b32 s91, s90, 8
	s_add_u32 s92, s34, s91
	s_addc_u32 s93, s35, 0
	s_add_u32 s92, s92, 0x1000
	s_addc_u32 s93, s93, 0
	s_add_u32 s94, s34, 0x3600
	s_addc_u32 s95, s35, 0
	s_lshl_b32 s91, s90, 7
	s_add_u32 s96, s94, s91
	s_addc_u32 s97, s95, 0
	v_mov_b32_e32 v253, 0
	v_mov_b32_e32 v252, 1
	s_waitcnt lgkmcnt(0)
	v_readfirstlane_b32 s98, v250
	v_readfirstlane_b32 s99, v251
	global_atomic_add v250, v253, v252, s[92:93] offset:1024 sc0
	s_mul_i32 s98, s98, 4
	s_mul_i32 s99, s99, 3
	s_waitcnt vmcnt(0)
	v_readfirstlane_b32 s91, v250
	s_add_i32 s91, s91, 1
	s_cmp_lg_u32 s91, s98
	s_cbranch_scc1 .Lfb3_poll
	buffer_wbl2 sc1
	s_waitcnt vmcnt(0)
	global_atomic_add v253, v252, s[94:95]
	global_atomic_add v253, v252, s[94:95] offset:128
	global_atomic_add v253, v252, s[94:95] offset:256
	global_atomic_add v253, v252, s[94:95] offset:384
	global_atomic_add v253, v252, s[94:95] offset:512
	global_atomic_add v253, v252, s[94:95] offset:640
	global_atomic_add v253, v252, s[94:95] offset:768
	global_atomic_add v253, v252, s[94:95] offset:896
	global_atomic_add v253, v252, s[94:95] offset:1024
	global_atomic_add v253, v252, s[94:95] offset:1152
	global_atomic_add v253, v252, s[94:95] offset:1280
	global_atomic_add v253, v252, s[94:95] offset:1408
	global_atomic_add v253, v252, s[94:95] offset:1536
	global_atomic_add v253, v252, s[94:95] offset:1664
	global_atomic_add v253, v252, s[94:95] offset:1792
	global_atomic_add v253, v252, s[94:95] offset:1920

; #define LAS __attribute__((address_space(3)))
; __device__ __forceinline__ void h3_phase(const Ptrs& P, LAS unsigned char* lds, int bx, int G, int tid) {
;     constexpr int QS = 136;
;     LAS unsigned short* Q1 = (LAS unsigned short*)lds;
;     LAS unsigned short* Q2 = Q1 + 64 * QS;
;     LAS unsigned short* KH = Q2 + 64 * QS;
;     LAS h16* FST = (LAS h16*)KH;
;     LAS h16* QST = FST + 64 * 128;
;     LAS unsigned short* Pm = KH + 160 * QS;
;     LAS unsigned short* VT = Pm + 64 * 72;
;     LAS float* tot = (LAS float*)(VT + 128 * 72);
;     LAS float* red = tot + 512;
;     LAS h16* GST = (LAS h16*)(red + 512);
;     LAS unsigned short* YST = (LAS unsigned short*)(GST + 64 * 128);
;     const int d = tid & 127, i = __builtin_amdgcn_readfirstlane(tid >> 7), lane = tid & 63, w = __builtin_amdgcn_readfirstlane(tid >> 6);
;     const int fr = lane & 15, fq = lane >> 4;
;     const int NIT = NCH * NH;
;     if (bx >= NIT) return;
;     h16x8 pf[2], pq[2], pv[2], pg[2]; bf16x8 psb[4];
;     ...
;     H3_PREFETCH(bx);
;     const bool hfix = (G & 15) == 0;
;     float l0 = P.lb_logits[(bx & 15) * HD + d], l1 = P.lb_logits[HW + (bx & 15) * HD + d], nwv = P.hgrn_nw[16 * w + fr];
;     size_t yoff = 0; bool have_y = false;
;     ...
;     for (int it = bx; it < NIT; it += G) {
.Lfb3_done:
	buffer_inv sc1
	s_waitcnt vmcnt(0)
.LBB0_350:
	s_or_b64 exec, exec, s[0:1]
	s_add_i32 s0, 0, 0x24018
	s_waitcnt lgkmcnt(0)
	v_mov_b32_e32 v0, s0
	s_add_i32 s0, 0, 0x24060
	s_barrier
	ds_read2_b64 v[0:3], v0 offset1:1
	v_mov_b32_e32 v4, s0
	ds_read_b64 v[4:5], v4
	s_and_b64 vcc, exec, s[4:5]
	s_waitcnt lgkmcnt(1)
	v_readfirstlane_b32 s45, v1
	v_readfirstlane_b32 s44, v0
	v_mbcnt_lo_u32_b32 v1, -1, 0
	v_mbcnt_hi_u32_b32 v1, -1, v1
	v_readfirstlane_b32 s1, v3
	v_or_b32_e32 v0, s33, v1
	v_readfirstlane_b32 s0, v2
	s_waitcnt lgkmcnt(0)
	v_readfirstlane_b32 s7, v5
	v_readfirstlane_b32 s8, v4
	v_readfirstlane_b32 s6, v0
	s_cbranch_vccz .LBB0_405
	s_add_u32 s68, s8, 0x14200000
	s_addc_u32 s69, s7, 0
	s_add_u32 s66, s8, 0x28200000
	s_addc_u32 s67, s7, 0
	s_ashr_i32 s70, s6, 6
	s_add_u32 s56, s8, 0x30200000
	s_addc_u32 s57, s7, 0
	s_lshl_b32 s8, s2, 2
	v_and_b32_e32 v79, 15, v1
	s_andn2_b32 s8, s8, 63
	s_lshl_b32 s7, s2, 7
	s_ashr_i32 s9, s8, 31
	v_lshl_or_b32 v76, s70, 4, v79
	s_lshl_b64 s[4:5], s[2:3], 15
	s_and_b32 s7, s7, 0x780
	s_lshl_b64 s[8:9], s[8:9], 14
	s_ashr_i32 s72, s6, 7
	v_ashrrev_i32_e32 v77, 31, v76
	v_lshl_add_u64 v[6:7], v[76:77], 2, s[0:1]
	s_add_u32 s0, s68, s8
	v_lshlrev_b32_e32 v62, 3, v0
	s_addc_u32 s1, s69, s9
	s_lshl_b32 s8, s7, 1
	v_and_b32_e32 v70, 0x78, v62
	v_add_u32_e32 v4, 0x200, v0
	s_add_u32 s0, s0, s8
	v_mov_b32_e32 v69, 0
	v_ashrrev_i32_e32 v52, 4, v4
	v_lshlrev_b32_e32 v4, 7, v76
	s_addc_u32 s1, s1, 0
	v_lshlrev_b32_e32 v68, 1, v70
	v_ashrrev_i32_e32 v2, 4, v0
	v_ashrrev_i32_e32 v5, 31, v4
	v_lshl_add_u64 v[20:21], s[0:1], 0, v[68:69]
	s_add_u32 s0, s56, s4
	v_bfe_u32 v1, v1, 4, 2
	v_ashrrev_i32_e32 v3, 31, v2
	s_mov_b64 s[46:47], 0x2000
	s_addc_u32 s1, s57, s5
	v_lshlrev_b64 v[54:55], 1, v[4:5]
	v_lshlrev_b64 v[72:73], 14, v[2:3]
	v_ashrrev_i32_e32 v53, 31, v52
	global_load_dword v77, v[6:7], off
	v_lshl_add_u64 v[6:7], v[20:21], 0, s[46:47]
	v_lshl_add_u64 v[4:5], s[0:1], 0, v[54:55]
	v_lshlrev_b32_e32 v56, 4, v1
	v_mov_b32_e32 v57, v69
	v_lshlrev_b64 v[74:75], 14, v[52:53]
	v_lshl_add_u64 v[8:9], v[6:7], 0, v[72:73]
	v_lshl_add_u64 v[4:5], v[4:5], 0, v[56:57]
	s_mov_b64 s[48:49], 0x3000
	v_lshl_add_u64 v[6:7], v[6:7], 0, v[74:75]
	global_load_dwordx4 v[16:19], v[8:9], off
	global_load_dwordx4 v[12:15], v[6:7], off
	global_load_dwordx4 v[36:39], v[4:5], off offset:192
	global_load_dwordx4 v[40:43], v[4:5], off offset:128
	global_load_dwordx4 v[44:47], v[4:5], off offset:64
	global_load_dwordx4 v[48:51], v[4:5], off
	v_lshl_add_u64 v[4:5], v[20:21], 0, s[48:49]
	v_lshl_add_u64 v[22:23], v[4:5], 0, v[74:75]
	s_mov_b64 s[50:51], 0x1000
	v_lshl_add_u64 v[24:25], v[4:5], 0, v[72:73]
	global_load_dwordx4 v[4:7], v[22:23], off
	global_load_dwordx4 v[8:11], v[24:25], off
	v_lshl_add_u64 v[22:23], v[20:21], 0, s[50:51]
	v_and_b32_e32 v71, 0x7f, v0
	v_lshl_add_u64 v[24:25], v[22:23], 0, v[74:75]
	v_lshl_add_u64 v[22:23], v[22:23], 0, v[72:73]
	v_lshl_add_u64 v[58:59], v[20:21], 0, v[74:75]
	global_load_dwordx4 v[28:31], v[24:25], off
	global_load_dwordx4 v[32:35], v[22:23], off
	v_lshl_add_u64 v[60:61], v[20:21], 0, v[72:73]
	global_load_dwordx4 v[20:23], v[58:59], off
	global_load_dwordx4 v[24:27], v[60:61], off
	v_or_b32_e32 v58, s7, v71
	s_add_i32 s0, 0, 0x19e00
	v_lshlrev_b32_e32 v58, 2, v58
	v_mov_b32_e32 v59, v69
	v_lshl_add_u32 v86, v71, 2, s0
	v_lshl_add_u64 v[60:61], s[44:45], 0, v[58:59]
	s_movk_i32 s0, 0x2000
	v_add_co_u32_e32 v60, vcc, s0, v60
	v_lshlrev_b32_e32 v63, 3, v1
	s_nop 0
	v_addc_co_u32_e32 v61, vcc, 0, v61, vcc
	global_load_dword v90, v[60:61], off
	global_load_dword v89, v58, s[44:45]
	v_lshlrev_b32_e32 v95, 2, v1
	v_lshlrev_b32_e32 v1, 9, v1
	s_add_i32 s59, 0, 0x1ae00
	s_add_i32 s60, 0, 0x1ee00
	v_or_b32_e32 v116, 1, v95
	v_add_lshl_u32 v1, v76, v1, 1
	v_add_u32_e32 v122, s59, v1
	v_add_u32_e32 v123, s60, v1
	v_lshlrev_b32_e32 v1, 7, v116
	v_or_b32_e32 v117, 2, v95
	v_add_lshl_u32 v1, v1, v76, 1
	v_add_u32_e32 v125, s59, v1
	v_add_u32_e32 v126, s60, v1
	v_lshlrev_b32_e32 v1, 7, v117
	v_or_b32_e32 v118, 3, v95
	v_add_lshl_u32 v1, v1, v76, 1
	v_add_u32_e32 v128, s59, v1
	v_add_u32_e32 v129, s60, v1
	v_lshlrev_b32_e32 v1, 7, v118
	v_add_lshl_u32 v1, v1, v76, 1
	s_add_i32 s58, 0, 0x1a600
	v_add_u32_e32 v131, s59, v1
	v_add_u32_e32 v132, s60, v1
	v_or_b32_e32 v1, 16, v95
	v_lshl_add_u32 v133, v1, 2, s58
	v_lshlrev_b32_e32 v1, 7, v1
	v_add_lshl_u32 v1, v1, v76, 1
	v_add_u32_e32 v134, s59, v1
	v_add_u32_e32 v135, s60, v1
	v_or_b32_e32 v1, 17, v95
	v_lshl_add_u32 v136, v1, 2, s58
	v_lshlrev_b32_e32 v1, 7, v1
	v_add_lshl_u32 v1, v1, v76, 1
	v_add_u32_e32 v137, s59, v1
	v_add_u32_e32 v138, s60, v1
	v_or_b32_e32 v1, 18, v95
	v_lshl_add_u32 v139, v1, 2, s58
	v_lshlrev_b32_e32 v1, 7, v1
	v_add_lshl_u32 v1, v1, v76, 1
	s_add_i32 s7, 0, 0x15600
	s_and_b32 s0, s6, 0x3fffff80
	s_lshl_b32 s22, s72, 4
	v_add_u32_e32 v140, s59, v1
	v_add_u32_e32 v141, s60, v1
	v_or_b32_e32 v1, 19, v95
	s_cmp_lt_i32 s70, 10
	v_lshl_add_u32 v142, v1, 2, s58
	v_lshlrev_b32_e32 v1, 7, v1
; __device__ __forceinline__ void h3_phase(const Ptrs& P, LAS unsigned char* lds, int bx, int G, int tid) {
;     ...
;     const int d = tid & 127, i = __builtin_amdgcn_readfirstlane(tid >> 7), lane = tid & 63, w = __builtin_amdgcn_readfirstlane(tid >> 6);
;     const int fr = lane & 15, fq = lane >> 4;
;     const int NIT = NCH * NH;
;     if (bx >= NIT) return;
;     h16x8 pf[2], pq[2], pv[2], pg[2]; bf16x8 psb[4];
;     ...
;     H3_PREFETCH(bx);
;     const bool hfix = (G & 15) == 0;
;     float l0 = P.lb_logits[(bx & 15) * HD + d], l1 = P.lb_logits[HW + (bx & 15) * HD + d], nwv = P.hgrn_nw[16 * w + fr];
;     size_t yoff = 0; bool have_y = false;
;     ...
;     for (int it = bx; it < NIT; it += G) {
;         const int n = it >> 4, h = it & 15, t0 = n * CH;
;         if (!hfix) { l0 = P.lb_logits[h * HD + d]; l1 = P.lb_logits[HW + h * HD + d]; }
;         tile_st(FST, pf, tid); tile_st(QST, pq, tid); vt_st(VT, pv, tid);
;         bf16x8 sb[4];
; #pragma unroll
;         for (int k2 = 0; k2 < 4; ++k2) sb[k2] = psb[k2];
;         __syncthreads();
;         const float oml = 1.f - __builtin_amdgcn_rcpf(1.f + __expf(l1 - l0));
;         float kk[16], pc[16], qq[16], run = 1.f;
; #pragma unroll
;         for (int u = 0; u < 16; ++u) { const float xv = (float)FST[(16 * i + u) * 128 + d]; qq[u] = (float)QST[(16 * i + u) * 128 + d];
;             const float k = oml * __builtin_amdgcn_rcpf(1.f + __expf(xv)); run *= (1.f - k); kk[u] = k; pc[u] = run; }
;         tot[i * 128 + d] = run;
;         for (int z = tid; z < 64 * 72 / 8; z += 512) ((LAS u32x4*)Pm)[z] = (u32x4){0u, 0u, 0u, 0u};
;         if (tid < 64) red[tid] = 0.f;
;         __syncthreads();
;         tile_st(GST, pg, tid);
;         {
;             float tt[4];
; #pragma unroll
;             for (int j = 0; j < 4; ++j) tt[j] = tot[j * 128 + d];
;             float er = 1.f;
; #pragma unroll
;             for (int j = 0; j < 4; ++j) if (j < i) er *= tt[j];
;             float erho[4];
; #pragma unroll
;             for (int ip = 0; ip < 4; ++ip) { float rho = 1.f;
; #pragma unroll
;                 for (int j = 0; j < 4; ++j) if (j >= i && j < ip) rho *= tt[j];
;                 erho[ip] = rho; }
;             float kd[16];
; #pragma unroll
;             for (int u = 0; u < 16; ++u) { const int t = 16 * i + u;
;                 const float q2 = qq[u] * pc[u]; kd[u] = kk[u] * __builtin_amdgcn_rcpf(pc[u]);
	s_cselect_b64 s[52:53], -1, 0
	s_add_i32 s61, 0, 0x13200
	v_add_lshl_u32 v1, v1, v76, 1
	s_movk_i32 s8, 0x90
	s_cmp_gt_i32 s72, 0
	v_add_u32_e32 v143, s59, v1
	v_add_u32_e32 v144, s60, v1
	v_or_b32_e32 v1, 32, v95
	v_mul_lo_u32 v64, v76, s8
	s_cselect_b64 s[8:9], -1, 0
	s_cmp_lt_i32 s72, 1
	v_lshl_add_u32 v145, v1, 2, s58
	v_lshlrev_b32_e32 v1, 7, v1
	s_cselect_b64 s[10:11], -1, 0
	s_cmp_gt_i32 s72, 1
	v_add_lshl_u32 v1, v1, v76, 1
	s_cselect_b64 s[12:13], -1, 0
	s_cmp_lt_i32 s72, 2
	v_add_u32_e32 v146, s59, v1
	v_add_u32_e32 v147, s60, v1
	v_or_b32_e32 v1, 33, v95
	s_cselect_b64 s[14:15], -1, 0
	s_cmp_gt_i32 s72, 2
	v_lshl_add_u32 v148, v1, 2, s58
	v_lshlrev_b32_e32 v1, 7, v1
	s_cselect_b64 s[16:17], -1, 0
	s_cmp_lt_i32 s72, 3
	v_add_lshl_u32 v1, v1, v76, 1
	v_lshlrev_b32_e32 v58, 4, v0
	s_cselect_b64 s[18:19], -1, 0
	s_cmp_gt_i32 s72, 3
	v_add_u32_e32 v149, s59, v1
	v_add_u32_e32 v150, s60, v1
	v_or_b32_e32 v1, 34, v95
	v_and_b32_e32 v59, 0xffffff00, v58
	s_cselect_b64 s[20:21], -1, 0
	s_cmp_lt_i32 s72, 4
	v_lshl_add_u32 v151, v1, 2, s58
	v_lshlrev_b32_e32 v1, 7, v1
	v_add3_u32 v87, 0, v68, v59
	v_add3_u32 v93, s59, v68, v59
	v_lshlrev_b32_e32 v59, 1, v71
	s_cselect_b64 s[54:55], -1, 0
	s_or_b32 s22, s22, 1
	v_add_lshl_u32 v1, v1, v76, 1
	v_add_u32_e32 v94, 0, v59
	v_lshl_or_b32 v59, s72, 12, v59
	s_mul_i32 s23, s72, 0x880
	s_mulk_i32 s22, 0x110
	v_add_u32_e32 v152, s59, v1
	v_add_u32_e32 v153, s60, v1
	v_or_b32_e32 v1, 35, v95
	v_add_u32_e32 v97, 0, v59
	v_or_b32_e32 v59, s23, v71
	s_add_i32 s23, s22, 0x110
	v_lshl_add_u32 v154, v1, 2, s58
	v_lshlrev_b32_e32 v1, 7, v1
	v_or_b32_e32 v66, 48, v95
	v_add_u32_e32 v100, s23, v94
	s_add_i32 s23, s22, 0x220
	v_add_lshl_u32 v1, v1, v76, 1
	v_add_u32_e32 v101, s23, v94
	s_add_i32 s23, s22, 0x330
	v_add_u32_e32 v155, s59, v1
	v_add_u32_e32 v156, s60, v1
	v_lshlrev_b32_e32 v1, 7, v66
	v_add_u32_e32 v102, s23, v94
	s_add_i32 s23, s22, 0x440
	v_add_lshl_u32 v1, v1, v76, 1
	v_add_u32_e32 v103, s23, v94
	s_add_i32 s23, s22, 0x550
	v_add_u32_e32 v157, s59, v1
	v_add_u32_e32 v158, s60, v1
	v_or_b32_e32 v1, 49, v95
	v_add_u32_e32 v104, s23, v94
	s_add_i32 s23, s22, 0x660
	v_lshl_add_u32 v159, v1, 2, s58
	v_lshlrev_b32_e32 v1, 7, v1
	v_add_u32_e32 v105, s23, v94
	s_add_i32 s23, s22, 0x770
	v_add_lshl_u32 v1, v1, v76, 1
	v_add_u32_e32 v106, s23, v94
	s_add_i32 s23, s22, 0x880
	v_add_u32_e32 v160, s59, v1
	v_add_u32_e32 v161, s60, v1
	v_or_b32_e32 v1, 50, v95
	v_bitop3_b32 v60, v62, v2, 56 bitop3:0x6c
	v_add_u32_e32 v64, s7, v64
	v_add_u32_e32 v108, s23, v94
	s_add_i32 s23, s22, 0x990
	v_lshlrev_b32_e32 v113, 8, v2
	v_lshlrev_b64 v[82:83], 13, v[2:3]
	v_bitop3_b32 v2, v76, v63, 56 bitop3:0x6c
	v_lshl_add_u32 v162, v1, 2, s58
	v_lshlrev_b32_e32 v1, 7, v1
	v_add_u32_e32 v109, s23, v94
	s_add_i32 s23, s22, 0xaa0
	v_lshl_add_u32 v119, v2, 1, v64
	v_or_b32_e32 v2, 32, v63
	v_add_lshl_u32 v1, v1, v76, 1
	v_add_u32_e32 v110, s23, v94
	s_add_i32 s23, s22, 0xbb0
	v_bitop3_b32 v2, v76, v2, 56 bitop3:0x6c
	v_add_u32_e32 v163, s59, v1
	v_add_u32_e32 v164, s60, v1
	v_or_b32_e32 v1, 51, v95
	v_bitop3_b32 v62, v52, v62, 56 bitop3:0x78
	v_add_u32_e32 v111, s23, v94
	s_add_i32 s23, s22, 0xcc0
	v_lshl_add_u32 v120, v2, 1, v64
	v_lshl_add_u32 v165, v1, 2, s58
	v_lshlrev_b32_e32 v1, 7, v1
	v_lshl_add_u64 v[2:3], s[56:57], 0, v[54:55]
	s_lshl_b32 s56, s70, 5
	v_lshl_add_u32 v60, v60, 1, s7
	v_mul_u32_u24_e32 v61, 0x90, v70
	v_lshl_add_u32 v62, v62, 1, s7
	v_lshl_add_u32 v91, s0, 2, v86
	s_movk_i32 s0, 0x240
	v_add_u32_e32 v78, 0, v56
	v_add_u32_e32 v65, s61, v56
	v_add_u32_e32 v99, s22, v94
	v_add_u32_e32 v112, s23, v94
	s_add_i32 s23, s22, 0xdd0
	s_addk_i32 s22, 0xee0
	v_lshlrev_b32_e32 v107, 8, v52
	v_lshlrev_b64 v[80:81], 13, v[52:53]
	v_mul_u32_u24_e32 v52, 0x110, v79
	v_mul_u32_u24_e32 v53, 0x90, v79
	v_add_lshl_u32 v1, v1, v76, 1
	v_add_u32_e32 v169, s61, v58
	s_add_i32 s61, s61, s56
	v_cmp_gt_i32_e64 s[0:1], s0, v0
	v_cmp_gt_i32_e64 s[4:5], 64, v0
	v_lshl_add_u32 v92, v0, 2, s58
	v_add_u32_e32 v88, s60, v68
	v_cmp_eq_u32_e64 s[6:7], 0, v79
	v_lshl_add_u32 v96, v66, 2, s58
	v_lshl_add_u32 v98, v59, 1, 0
	s_movk_i32 s71, 0x110
	v_add_u32_e32 v114, s23, v94
	v_add_u32_e32 v115, s22, v94
	s_mulk_i32 s72, 0x1100
	v_cmp_gt_u32_e64 s[22:23], v79, v95
	v_cmp_gt_u32_e64 s[24:25], v79, v116
	v_cmp_gt_u32_e64 s[26:27], v79, v117
	v_cmp_gt_u32_e64 s[28:29], v79, v118
	v_add_u32_e32 v121, s58, v56
	v_lshl_add_u32 v124, v116, 2, s58
	v_lshl_add_u32 v127, v117, 2, s58
	v_lshl_add_u32 v130, v118, 2, s58
	v_add_u32_e32 v166, s59, v1
	v_add_u32_e32 v167, s60, v1
	v_lshl_add_u64 v[84:85], v[2:3], 0, v[56:57]
	v_add_u32_e32 v168, 0xfffffe00, v0
	v_lshl_add_u32 v170, v79, 1, s61
	s_mov_b64 s[60:61], 0
	s_mov_b64 s[58:59], 0
	v_add_u32_e32 v171, v60, v61
	v_add_u32_e32 v172, v62, v61
	v_add_u32_e32 v173, v78, v52
	v_add_u32_e32 v174, v65, v53
	v_mov_b32_e32 v175, 0x358637bd
	s_mov_b32 s73, 0x800000
	v_mov_b32_e32 v0, v69
	v_mov_b32_e32 v1, v69
	v_mov_b32_e32 v2, v69
	v_mov_b32_e32 v3, v69
	s_mov_b32 s75, s2
	s_branch .LBB0_353

; #define LAS __attribute__((address_space(3)))
; __device__ __forceinline__ unsigned xb_ld(unsigned* p)              { return __hip_atomic_load(p, __ATOMIC_RELAXED, __HIP_MEMORY_SCOPE_AGENT); }
; __device__ __forceinline__ unsigned xb_add(unsigned* p, unsigned v) { return __hip_atomic_fetch_add(p, v, __ATOMIC_RELAXED, __HIP_MEMORY_SCOPE_AGENT); }
; __device__ __forceinline__ unsigned xb_xcc_id() { return (unsigned)__builtin_amdgcn_s_getreg((3 << 11) | 20) & 0xFu; }
; #define XB_SPIN(cond, bar) do { unsigned _sp = 0; while (cond) { __builtin_amdgcn_s_sleep(1); \
;     if ((++_sp & 255u) == 0u) { if (xb_ld(&(bar)[XB_TMO])) break; if (_sp > XB_SPIN_CAP) { atomicAdd(&(bar)[XB_TMO], 1u); break; } } } } while (0)
; __device__ __forceinline__ void xcd_barrier(unsigned* bar, volatile LAS unsigned* st, bool is_t0) {
;     asm volatile("s_waitcnt vmcnt(0)" ::: "memory");
;     __syncthreads();
;     if (is_t0) {
;         __builtin_amdgcn_s_waitcnt(0);
;         const unsigned x = xb_xcc_id();
;         unsigned nloc = st[0], nx = st[1];
;         if (nloc == 0u) { xcd_barrier_complete(bar, x, nloc, nx); st[0] = nloc; st[1] = nx; }
;         const unsigned old = xb_add(&bar[XB_XSUB(x)], 1u);
;         const unsigned gen = old / nloc;
;         if (old + 1u == (gen + 1u) * nloc) {
;             __builtin_amdgcn_fence(__ATOMIC_RELEASE, "agent");
;             asm volatile("s_waitcnt vmcnt(0)" ::: "memory");
;             const unsigned og = xb_add(&bar[XB_TOP], 1u);
;             const unsigned tg = og / nx;
;             if (og + 1u == (tg + 1u) * nx) xb_add(&bar[XB_TOPGEN], 1u);
;             else XB_SPIN(xb_ld(&bar[XB_TOPGEN]) == tg, bar);
;             __builtin_amdgcn_fence(__ATOMIC_ACQUIRE, "agent");
;             xb_add(&bar[XB_XGEN(x)], 1u);
;             asm volatile("s_waitcnt vmcnt(0)" ::: "memory");
;         } else {
;             XB_SPIN(xb_ld(&bar[XB_XGEN(x)]) == gen, bar);
;             __builtin_amdgcn_fence(__ATOMIC_ACQUIRE, "agent");
;             asm volatile("s_waitcnt vmcnt(0)" ::: "memory");
;         }
;     }
;     __syncthreads();
.LBB0_405:
	s_barrier
	v_mbcnt_lo_u32_b32 v0, -1, 0
	v_mbcnt_hi_u32_b32 v0, -1, v0
	s_waitcnt vmcnt(0)
	s_nop 0
	v_cmp_eq_u32_e32 vcc, 0, v0
	s_and_b64 s[0:1], vcc, s[36:37]
	s_barrier
	s_and_saveexec_b64 s[4:5], s[0:1]
	s_xor_b64 s[0:1], exec, s[4:5]
	s_cbranch_execz .LBB0_458
	s_waitcnt vmcnt(0) expcnt(0) lgkmcnt(0)
	v_mov_b32_e32 v250, 0x24080
	ds_read_b64 v[250:251], v250
	s_getreg_b32 s90, hwreg(HW_REG_XCC_ID, 0, 4)
	s_and_b32 s90, s90, 15
	s_lshl_b32 s91, s90, 8
	s_add_u32 s92, s34, s91
	s_addc_u32 s93, s35, 0
	s_add_u32 s92, s92, 0x1000
	s_addc_u32 s93, s93, 0
	s_add_u32 s94, s34, 0x3600
	s_addc_u32 s95, s35, 0
	s_lshl_b32 s91, s90, 7
	s_add_u32 s96, s94, s91
	s_addc_u32 s97, s95, 0
	v_mov_b32_e32 v253, 0
	v_mov_b32_e32 v252, 1
	s_waitcnt lgkmcnt(0)
	v_readfirstlane_b32 s98, v250
	v_readfirstlane_b32 s99, v251
	global_atomic_add v250, v253, v252, s[92:93] offset:1024 sc0
	s_mul_i32 s98, s98, 5
	s_mul_i32 s99, s99, 4
	s_waitcnt vmcnt(0)
	v_readfirstlane_b32 s91, v250
	s_add_i32 s91, s91, 1
	s_cmp_lg_u32 s91, s98
	s_cbranch_scc1 .Lfb4_poll
	buffer_wbl2 sc1
	s_waitcnt vmcnt(0)
	global_atomic_add v253, v252, s[94:95]
	global_atomic_add v253, v252, s[94:95] offset:128
	global_atomic_add v253, v252, s[94:95] offset:256
	global_atomic_add v253, v252, s[94:95] offset:384
	global_atomic_add v253, v252, s[94:95] offset:512
	global_atomic_add v253, v252, s[94:95] offset:640
	global_atomic_add v253, v252, s[94:95] offset:768
	global_atomic_add v253, v252, s[94:95] offset:896
	global_atomic_add v253, v252, s[94:95] offset:1024
	global_atomic_add v253, v252, s[94:95] offset:1152
	global_atomic_add v253, v252, s[94:95] offset:1280
	global_atomic_add v253, v252, s[94:95] offset:1408
	global_atomic_add v253, v252, s[94:95] offset:1536
	global_atomic_add v253, v252, s[94:95] offset:1664
	global_atomic_add v253, v252, s[94:95] offset:1792
	global_atomic_add v253, v252, s[94:95] offset:1920

; #define LAS __attribute__((address_space(3)))
; #define PG8_STAGE(bufoff, gbase) do { _Pragma("unroll") for (int _i = 0; _i < 2; ++_i) \
;         __builtin_amdgcn_global_load_lds((const unsigned*)((const char*)(gbase) + voffA[_i]), (LAS unsigned*)(lds + (bufoff) + ldsw + _i * 8192), 16, 0, 0); } while (0)
; #define PG8_WAIT_V(n) asm volatile("s_waitcnt vmcnt(" #n ")" ::: "memory")
; #define PG8_BAR __builtin_amdgcn_s_barrier()
; template <class Epi, class Sched, bool FP8 = false>
; __device__ __forceinline__ void gemm_phase(LAS unsigned char* lds, const Gemm g, const Sched& S, const Epi& E, const int tid) {
;     const int wid = __builtin_amdgcn_readfirstlane(tid >> 6), lane = tid & 63, wr = wid >> 2, wc = wid & 3, fr = lane & 15, fq = lane >> 4;
;     const int K = g.K, nt = g.Kloop / BK;
;     const size_t halfb = (size_t)g.Kloop * 2;
;     const int sc8 = 0x7f7f7f7f;
;     unsigned voffA[2];
; #pragma unroll
;     for (int i = 0; i < 2; ++i) { int R, C; stage_rc(tid * 16 + i * 8192, R, C); voffA[i] = (unsigned)(R * K + C) * 2u; }
;     const size_t kstep = (size_t)(BK * 2);
;     const size_t hstep = (size_t)HALF * K * 2;
;     const size_t tstep = 2 * hstep;
;     const unsigned ldsw = (unsigned)wid * 1024u;
;     const int aoff = lds_byte(wr * 64 + fr, fq * 8), boff = lds_byte(wc * 32 + fr, fq * 8);
;     ...
;     Unit cur, nxt; int ui = 0;
;     if (!S.next(0, cur)) return;
;     f32x4 acc[2][2][4][2];
; #pragma unroll
;     for (int a = 0; a < 2; ++a)
; #pragma unroll
;         for (int b = 0; b < 2; ++b)
; #pragma unroll
;             for (int m = 0; m < 4; ++m)
; #pragma unroll
;                 for (int n = 0; n < 2; ++n) acc[a][b][m][n] = (f32x4){0.f, 0.f, 0.f, 0.f};
;     h16x8 At[4][2], B0[2][2], B1[2][2];
;     const char* cA = (const char*)g.A + (size_t)cur.pm * tstep + cur.half * halfb; const char* cB = (const char*)g.Bt + (size_t)cur.pn * tstep + cur.half * halfb;
;     PG8_STAGE(PG8_SB(0, 0), cB); PG8_STAGE(PG8_SB(0, 1), cB + hstep); PG8_STAGE(PG8_SA(0, 0), cA); PG8_STAGE(PG8_SA(0, 1), cA + hstep);
;     if (wr == 1) PG8_BAR;
;     PG8_WAIT_V(2); PG8_BAR;
;     PG8_STAGE(PG8_SB(1, 0), cB + kstep); PG8_STAGE(PG8_SA(1, 0), cA + kstep); PG8_STAGE(PG8_SB(1, 1), cB + hstep + kstep);
;     PG8_WAIT_V(6); PG8_BAR;
.Lfb4_done:
	buffer_inv sc1
	s_waitcnt vmcnt(0)
.LBB0_458:
	s_or_b64 exec, exec, s[0:1]
	s_cmpk_lt_i32 s2, 0x200
	s_cselect_b64 s[6:7], -1, 0
	s_add_i32 s0, 0, 0x24060
	s_waitcnt lgkmcnt(0)
	v_mov_b32_e32 v0, s0
	s_barrier
	ds_read_b64 v[0:1], v0
	v_mbcnt_lo_u32_b32 v12, -1, 0
	v_mbcnt_hi_u32_b32 v12, -1, v12
	s_and_b64 vcc, exec, s[6:7]
	s_waitcnt lgkmcnt(0)
	v_readfirstlane_b32 s12, v0
	v_or_b32_e32 v0, s33, v12
	v_readfirstlane_b32 s13, v1
	v_readfirstlane_b32 s1, v0
	s_cbranch_vccz .LBB0_488
	v_lshlrev_b32_e32 v1, 4, v0
	v_add_u32_e32 v2, 0x2000, v1
	v_ashrrev_i32_e32 v3, 31, v2
	v_lshrrev_b32_e32 v3, 22, v3
	v_add_u32_e32 v3, v2, v3
	v_ashrrev_i32_e32 v8, 10, v3
	v_mul_i32_i24_e32 v4, 0x400, v8
	v_sub_u32_e32 v2, v2, v4
	v_lshrrev_b32_e32 v4, 4, v2
	v_bitop3_b32 v2, v4, v2, 32 bitop3:0x6c
	v_ashrrev_i32_e32 v4, 31, v2
	v_lshrrev_b32_e32 v4, 26, v4
	v_add_u32_e32 v4, v2, v4
	s_add_u32 s50, s12, 0xc200000
	v_ashrrev_i32_e32 v9, 6, v4
	v_and_b32_e32 v4, 0xc0, v4
	s_addc_u32 s51, s13, 0
	v_sub_u32_e32 v2, v2, v4
	v_mov_b32_e32 v4, 1
	s_add_u32 s52, s12, 0x28200000
	v_lshlrev_b32_e32 v3, 5, v8
	v_ashrrev_i16_sdwa v2, v4, sext(v2) dst_sel:DWORD dst_unused:UNUSED_PAD src0_sel:DWORD src1_sel:BYTE_0
	s_addc_u32 s53, s13, 0
	s_ashr_i32 s14, s1, 6
	v_and_b32_e32 v3, 32, v3
	v_bfe_i32 v10, v2, 0, 16
	s_ashr_i32 s18, s1, 8
	s_lshl_b32 s54, s14, 10
	v_add_u32_e32 v2, v3, v10
	v_lshlrev_b32_e32 v3, 3, v8
	s_lshl_b32 s8, s65, 6
	v_and_b32_e32 v3, 0x7fff0, v3
	s_mul_i32 s0, s65, 0x41
	s_and_b64 s[4:5], s[40:41], exec
	v_add_lshl_u32 v3, v9, v3, 13
	s_cselect_b32 s0, s0, s8
	v_lshl_add_u32 v128, v2, 1, v3
	v_ashrrev_i32_e32 v2, 31, v0
	s_add_i32 s0, s0, s64
	v_lshrrev_b32_e32 v2, 26, v2
	s_ashr_i32 s4, s0, 31
	v_add_u32_e32 v2, v0, v2
	v_bfe_i32 v0, v0, 27, 1
	s_lshr_b32 s4, s4, 26
	v_lshrrev_b32_e32 v0, 22, v0
	s_add_i32 s4, s0, s4
	v_add_u32_e32 v0, v1, v0
	s_ashr_i32 s5, s4, 6
	s_and_b32 s4, s4, 0xffc0
	v_and_b32_e32 v0, 0xfffffc00, v0
	s_sub_i32 s4, s0, s4
	v_sub_u32_e32 v0, v1, v0
	s_bfe_i32 s0, s4, 0x80000
	v_lshrrev_b32_e32 v1, 4, v0
	s_bfe_u32 s0, s0, 0x2000d
	v_bitop3_b32 v0, v1, v0, 32 bitop3:0x6c
	s_add_i32 s8, s4, s0
	v_ashrrev_i32_e32 v1, 31, v0
	s_bfe_i32 s0, s8, 0x80000
	s_and_b32 s8, s8, 0xfc
	v_lshrrev_b32_e32 v1, 26, v1
	s_sub_i32 s4, s4, s8
	v_add_u32_e32 v1, v0, v1
	s_lshl_b32 s5, s5, 2
	s_sext_i32_i16 s0, s0
	s_sext_i32_i8 s4, s4
	v_ashrrev_i32_e32 v13, 6, v1
	v_and_b32_e32 v1, 0xc0, v1
	s_lshr_b32 s0, s0, 2
	s_add_i32 s44, s5, s4
	v_ashrrev_i32_e32 v11, 6, v2
	v_sub_u32_e32 v0, v0, v1
	s_ashr_i32 s45, s44, 31
	s_bfe_i64 s[8:9], s[0:1], 0x100000
	v_lshlrev_b32_e32 v2, 5, v11
	v_ashrrev_i16_sdwa v0, v4, sext(v0) dst_sel:DWORD dst_unused:UNUSED_PAD src0_sel:DWORD src1_sel:BYTE_0
	v_lshlrev_b32_e32 v1, 3, v11
	s_lshl_b64 s[4:5], s[44:45], 21
	s_lshl_b64 s[8:9], s[8:9], 21
	v_and_b32_e32 v2, 32, v2
	v_bfe_i32 v14, v0, 0, 16
	v_and_b32_e32 v1, 0x7fff0, v1
	s_add_u32 s46, s50, s8
	v_add_u32_e32 v0, v2, v14
	v_add_lshl_u32 v1, v13, v1, 13
	s_addc_u32 s47, s51, s9
	s_add_i32 s55, s54, 0
	v_lshl_add_u32 v130, v0, 1, v1
	v_mbcnt_lo_u32_b32 v239, -1, 0
	v_mbcnt_hi_u32_b32 v239, -1, v239
	s_lshr_b32 s92, s33, 6
	s_lshl_b32 s93, s92, 3
	s_and_b32 s94, s92, 1
	s_lshl_b32 s94, s94, 2
	v_lshrrev_b32_e32 v236, 3, v239
	v_add_u32_e32 v236, s93, v236
	v_lshrrev_b32_e32 v237, 4, v239
	v_add_u32_e32 v237, s94, v237
	v_and_b32_e32 v238, 7, v239
	v_xor_b32_e32 v237, v238, v237
	v_lshlrev_b32_e32 v237, 4, v237
	v_lshl_add_u32 v130, v236, 13, v237
	v_add_u32_e32 v128, 0x80000, v130
	s_add_i32 m0, s55, 0x10000
	v_mov_b32_e32 v133, 0
	global_load_lds_dwordx4 v130, s[46:47]
	s_add_i32 m0, s55, 0x12000
	s_add_u32 s8, s46, 0x100000
	global_load_lds_dwordx4 v128, s[46:47]
	s_addc_u32 s9, s47, 0
	s_add_i32 m0, s55, 0x14000
	v_mov_b32_e32 v131, v133
	global_load_lds_dwordx4 v130, s[8:9]
	s_add_i32 m0, s55, 0x16000
	s_add_u32 s4, s52, s4
	s_addc_u32 s5, s53, s5
	s_add_i32 s56, s55, 0x2000
	global_load_lds_dwordx4 v128, s[8:9]
	s_mov_b32 m0, s55
	s_add_u32 s8, s4, 0x100000
	global_load_lds_dwordx4 v130, s[4:5]
	s_mov_b32 m0, s56
	s_addc_u32 s9, s5, 0
	s_add_i32 s57, s55, 0x4000
	global_load_lds_dwordx4 v128, s[4:5]
	s_mov_b32 m0, s57
	s_add_i32 s58, s55, 0x6000
	global_load_lds_dwordx4 v130, s[8:9]
	s_mov_b32 m0, s58
	v_mov_b32_e32 v129, v133
	global_load_lds_dwordx4 v128, s[8:9]
	s_cmp_eq_u32 s18, 1
	s_movk_i32 s59, 0x2000
	v_lshl_add_u64 v[6:7], s[46:47], 0, v[130:131]
	v_lshl_add_u64 v[4:5], s[46:47], 0, v[128:129]
	s_mov_b64 s[8:9], 0x100000
	v_lshl_add_u64 v[2:3], s[4:5], 0, v[130:131]
	v_lshl_add_u64 v[0:1], s[4:5], 0, v[128:129]
	s_cselect_b64 s[10:11], -1, 0
	s_cmp_lg_u32 s18, 1
	s_movk_i32 s60, 0x4000
	s_cbranch_scc1 .LBB0_461
	s_barrier

; #define LAS __attribute__((address_space(3)))
; __device__ __forceinline__ unsigned xb_ld(unsigned* p)              { return __hip_atomic_load(p, __ATOMIC_RELAXED, __HIP_MEMORY_SCOPE_AGENT); }
; __device__ __forceinline__ unsigned xb_add(unsigned* p, unsigned v) { return __hip_atomic_fetch_add(p, v, __ATOMIC_RELAXED, __HIP_MEMORY_SCOPE_AGENT); }
; __device__ __forceinline__ unsigned xb_xcc_id() { return (unsigned)__builtin_amdgcn_s_getreg((3 << 11) | 20) & 0xFu; }
; #define XB_SPIN(cond, bar) do { unsigned _sp = 0; while (cond) { __builtin_amdgcn_s_sleep(1); \
;     if ((++_sp & 255u) == 0u) { if (xb_ld(&(bar)[XB_TMO])) break; if (_sp > XB_SPIN_CAP) { atomicAdd(&(bar)[XB_TMO], 1u); break; } } } } while (0)
; __device__ __forceinline__ void xcd_barrier(unsigned* bar, volatile LAS unsigned* st, bool is_t0) {
;     asm volatile("s_waitcnt vmcnt(0)" ::: "memory");
;     __syncthreads();
;     if (is_t0) {
;         __builtin_amdgcn_s_waitcnt(0);
;         const unsigned x = xb_xcc_id();
;         unsigned nloc = st[0], nx = st[1];
;         if (nloc == 0u) { xcd_barrier_complete(bar, x, nloc, nx); st[0] = nloc; st[1] = nx; }
;         const unsigned old = xb_add(&bar[XB_XSUB(x)], 1u);
;         const unsigned gen = old / nloc;
;         if (old + 1u == (gen + 1u) * nloc) {
;             __builtin_amdgcn_fence(__ATOMIC_RELEASE, "agent");
;             asm volatile("s_waitcnt vmcnt(0)" ::: "memory");
;             const unsigned og = xb_add(&bar[XB_TOP], 1u);
;             const unsigned tg = og / nx;
;             if (og + 1u == (tg + 1u) * nx) xb_add(&bar[XB_TOPGEN], 1u);
;             else XB_SPIN(xb_ld(&bar[XB_TOPGEN]) == tg, bar);
;             __builtin_amdgcn_fence(__ATOMIC_ACQUIRE, "agent");
;             xb_add(&bar[XB_XGEN(x)], 1u);
;             asm volatile("s_waitcnt vmcnt(0)" ::: "memory");
;         } else {
;             XB_SPIN(xb_ld(&bar[XB_XGEN(x)]) == gen, bar);
;             __builtin_amdgcn_fence(__ATOMIC_ACQUIRE, "agent");
;             asm volatile("s_waitcnt vmcnt(0)" ::: "memory");
;         }
;     }
;     __syncthreads();
.LBB0_488:
	v_mbcnt_lo_u32_b32 v0, -1, 0
	v_mbcnt_hi_u32_b32 v0, -1, v0
	s_waitcnt vmcnt(0)
	s_nop 0
	v_cmp_eq_u32_e32 vcc, 0, v0
	s_and_b64 s[0:1], vcc, s[36:37]
	s_barrier
	s_and_saveexec_b64 s[4:5], s[0:1]
	s_xor_b64 s[0:1], exec, s[4:5]
	s_cbranch_execz .LBB0_541
	s_waitcnt vmcnt(0) expcnt(0) lgkmcnt(0)
	v_mov_b32_e32 v250, 0x24080
	ds_read_b64 v[250:251], v250
	s_getreg_b32 s90, hwreg(HW_REG_XCC_ID, 0, 4)
	s_and_b32 s90, s90, 15
	s_lshl_b32 s91, s90, 8
	s_add_u32 s92, s34, s91
	s_addc_u32 s93, s35, 0
	s_add_u32 s92, s92, 0x1000
	s_addc_u32 s93, s93, 0
	s_add_u32 s94, s34, 0x3600
	s_addc_u32 s95, s35, 0
	s_lshl_b32 s91, s90, 7
	s_add_u32 s96, s94, s91
	s_addc_u32 s97, s95, 0
	v_mov_b32_e32 v253, 0
	v_mov_b32_e32 v252, 1
	s_waitcnt lgkmcnt(0)
	v_readfirstlane_b32 s98, v250
	v_readfirstlane_b32 s99, v251
	global_atomic_add v250, v253, v252, s[92:93] offset:1024 sc0
	s_mul_i32 s98, s98, 6
	s_mul_i32 s99, s99, 5
	s_waitcnt vmcnt(0)
	v_readfirstlane_b32 s91, v250
	s_add_i32 s91, s91, 1
	s_cmp_lg_u32 s91, s98
	s_cbranch_scc1 .Lfb5_poll
	buffer_wbl2 sc1
	s_waitcnt vmcnt(0)
	global_atomic_add v253, v252, s[94:95]
	global_atomic_add v253, v252, s[94:95] offset:128
	global_atomic_add v253, v252, s[94:95] offset:256
	global_atomic_add v253, v252, s[94:95] offset:384
	global_atomic_add v253, v252, s[94:95] offset:512
	global_atomic_add v253, v252, s[94:95] offset:640
	global_atomic_add v253, v252, s[94:95] offset:768
	global_atomic_add v253, v252, s[94:95] offset:896
	global_atomic_add v253, v252, s[94:95] offset:1024
	global_atomic_add v253, v252, s[94:95] offset:1152
	global_atomic_add v253, v252, s[94:95] offset:1280
	global_atomic_add v253, v252, s[94:95] offset:1408
	global_atomic_add v253, v252, s[94:95] offset:1536
	global_atomic_add v253, v252, s[94:95] offset:1664
	global_atomic_add v253, v252, s[94:95] offset:1792
	global_atomic_add v253, v252, s[94:95] offset:1920

; #define REP(k) for (int rep_ = 0; rep_ < (((REPMASK >> (k)) & 1) ? 2 : 1); ++rep_)
; #define fresh_tid() ((wave0 << 6) | lane_id_fresh())
; #define SEAM(k) do { if constexpr (COOP) { if (IN(k) && IN((k) + 1)) { if ((k) == CG_SEAM) cg::this_grid().sync(); else xcd_barrier(xbar, xst, lane_id_fresh() == 0 && wave0 == 0); } } } while (0)
; template <int COOP>
; __global__ void __launch_bounds__(512, 2) mega(Args a) {
;     ...
;     SEAM(4);
;     if (IN(5)) REP(5) { const Ptrs P = mkptrs(ptab);
;         pg8::Gemm g{P.YAB, P.WABT, T, D, 4096, HW}; pg8::StaticOrder S; S.init(T, D, G, bx, 2, 4);
;         pg8::EpiG2 E{P.PG, P.MG};
;         pg8::gemm_phase(lds, g, S, E, fresh_tid());
;     }
;     SEAM(5);
;     if (IN(6)) { const Ptrs P = mkptrs(ptab);
;         pg8::Gemm g{P.MG, P.WOT, T, D, D, D}; pg8::StaticOrder S; S.init(T, D, G, bx, 1, 4);
;         pg8::EpiG3 E{P.x, P.U, P.ssq, P.cnt};
;         pg8::gemm_phase(lds, g, S, E, fresh_tid());
.Lfb5_done:
	buffer_inv sc1
	s_waitcnt vmcnt(0)
.LBB0_541:
	s_or_b64 exec, exec, s[0:1]
	s_add_i32 s0, 0, 0x24000
	s_waitcnt lgkmcnt(0)
	v_mov_b32_e32 v0, s0
	s_barrier
	ds_read_b64 v[4:5], v0
	s_add_i32 s0, 0, 0x24050
	v_mov_b32_e32 v0, s0
	s_add_i32 s0, 0, 0x24060
	ds_read_b128 v[0:3], v0
	s_waitcnt lgkmcnt(1)
	v_readfirstlane_b32 s12, v4
	v_mov_b32_e32 v4, s0
	v_readfirstlane_b32 s13, v5
	ds_read_b64 v[4:5], v4
	s_waitcnt lgkmcnt(1)
	v_readfirstlane_b32 s21, v1
	v_readfirstlane_b32 s20, v0
	v_mbcnt_lo_u32_b32 v8, -1, 0
	v_mbcnt_hi_u32_b32 v8, -1, v8
	v_cndmask_b32_e64 v1, 0, 1, s[6:7]
	v_or_b32_e32 v0, s33, v8
	v_readfirstlane_b32 s9, v3
	v_readfirstlane_b32 s8, v2
	s_waitcnt lgkmcnt(0)
	v_readfirstlane_b32 s11, v5
	v_readfirstlane_b32 s10, v4
	v_cmp_ne_u32_e64 s[0:1], 1, v1
	s_andn2_b64 vcc, exec, s[6:7]
	v_readfirstlane_b32 s6, v0
	s_cbranch_vccnz .LBB0_547
	s_and_b64 vcc, exec, s[38:39]
	s_cbranch_vccz .LBB0_544
	s_lshl_b32 s7, s65, 6
	s_cbranch_execz .LBB0_545
	s_branch .LBB0_546
